# PF: row-scale staging deferred to the top of K iteration 1 (stats loads retire behind the first iteration's counted waits instead of a vmcnt(0) before the K loop)
# speedup vs baseline: 1.0095x; 1.0095x over previous
; __device__ __forceinline__ float rsq(float x) { return __builtin_amdgcn_rsqf(x); }
; __device__ __forceinline__ float sum4(f32x4 v) { return (v[0] + v[1]) + (v[2] + v[3]); }
; __global__ void __launch_bounds__(512, 2) fwd_kernel(Args args) {
;     ...
;                         for (int e = 0; e < 8; ++e) { const int row = pm * 256 + r0_ + 8 * e;
;                             const f32x4* sp = (const f32x4*)(stp + (size_t)row * 8);
;                             rsv[e] = rsq((sum4(sp[0]) + sum4(sp[1])) * (1.0f / SW) + EPS);
.LBB0_309:
	s_add_i32 s5, s5, 1
	s_load_dwordx2 s[100:101], s[0:1], 0xc8
	v_and_b32_e32 v232, 0xff, v209
	v_lshlrev_b32_e32 v233, 5, v232
	s_lshl_b32 vcc_lo, s77, 13
	s_waitcnt lgkmcnt(0)
	s_add_u32 s100, s100, 0x1200000
	s_addc_u32 s101, s101, 0
	s_add_u32 s100, s100, vcc_lo
	s_addc_u32 s101, s101, 0
	global_load_dwordx4 v[224:227], v233, s[100:101]
	global_load_dwordx4 v[228:231], v233, s[100:101] offset:16
	v_readlane_b32 s42, v254, 9
	s_mul_i32 s42, s5, s42
	s_waitcnt lgkmcnt(0)
	s_mul_hi_u32 s43, s5, s85
	s_add_i32 s43, s43, s42
	s_mul_i32 s42, s5, s85
	s_add_u32 s54, s42, s2
	s_addc_u32 s55, s43, s3
	v_mov_b64_e32 v[0:1], 0x3ff
	v_cmp_gt_i64_e32 vcc, s[54:55], v[0:1]
	v_cmp_lt_i64_e64 s[42:43], s[54:55], v[244:245]
	s_cbranch_vccnz .LBB0_315
	s_ashr_i32 s52, s54, 31
	s_lshr_b32 s52, s52, 29
	s_add_i32 s56, s54, s52
	s_and_b32 s52, s56, -8
	s_sub_i32 s57, s54, s52
	s_cmp_gt_i32 s57, -1
	s_mov_b64 s[54:55], -1
	s_cbranch_scc0 .LBB0_312
	s_lshl_b32 s58, s57, 7
	s_mov_b64 s[54:55], 0

; __device__ __forceinline__ float rsq(float x) { return __builtin_amdgcn_rsqf(x); }
; __device__ __forceinline__ float sum4(f32x4 v) { return (v[0] + v[1]) + (v[2] + v[3]); }
; __global__ void __launch_bounds__(512, 2) fwd_kernel(Args args) {
;     ...
;                         for (int e = 0; e < 8; ++e) { const int row = pm * 256 + r0_ + 8 * e;
;                             const f32x4* sp = (const f32x4*)(stp + (size_t)row * 8);
;                             rsv[e] = rsq((sum4(sp[0]) + sum4(sp[1])) * (1.0f / SW) + EPS);
.LBB0_316:
	s_cmp_lg_u32 s92, 0
	s_cbranch_scc1 .Lpf_nostage
	s_waitcnt vmcnt(8)
	s_and_b32 vcc_lo, s5, 1
	s_mul_i32 vcc_lo, vcc_lo, 0x3800
	s_add_i32 vcc_lo, vcc_lo, 0x20000
	v_lshl_add_u32 v233, v232, 2, vcc_lo
	v_add_f32_e32 v224, v224, v225
	v_add_f32_e32 v226, v226, v227
	v_add_f32_e32 v224, v224, v226
	v_add_f32_e32 v228, v228, v229
	v_add_f32_e32 v230, v230, v231
	v_add_f32_e32 v228, v228, v230
	v_add_f32_e32 v224, v224, v228
	v_fmamk_f32 v224, v224, 0x3b000000, v241
	v_rsq_f32_e32 v224, v224
	s_nop 1
	ds_write_b32 v233, v224
